# job3 loop: QK as one 18-MFMA accumulation chain (8 merge adds dropped) with 3-deep LDS operand prefetch
# speedup vs baseline: 1.0504x; 1.0067x over previous
.LBB0_939:
	s_add_i32 s12, s11, 0xffffff80
	v_add_u32_e32 v205, v226, v204
	v_cmp_lt_i32_e32 vcc, s12, v227
	s_waitcnt lgkmcnt(0)
	s_barrier
	s_waitcnt vmcnt(7)
	ds_write_b128 v205, v[166:169]
	s_waitcnt vmcnt(6)
	ds_write_b128 v205, v[170:173] offset:9472
	s_waitcnt vmcnt(5)
	ds_write_b128 v205, v[174:177] offset:18944
	s_waitcnt vmcnt(4)
	ds_write_b128 v205, v[178:181] offset:28416
	s_waitcnt vmcnt(3)
	ds_write_b128 v205, v[182:185] offset:37888
	s_waitcnt vmcnt(2)
	ds_write_b128 v205, v[186:189] offset:47360
	s_waitcnt vmcnt(1)
	ds_write_b128 v205, v[190:193] offset:56832
	s_waitcnt vmcnt(0)
	ds_write_b128 v228, v[194:197]
	s_and_saveexec_b64 s[6:7], vcc
	v_add_u32_e32 v148, v225, v210
	ds_write_b128 v148, v[162:165] offset:512
	s_or_b64 exec, exec, s[6:7]
	s_add_u32 s60, s34, 0x16d10000
	s_addc_u32 s61, s35, 0
	s_waitcnt lgkmcnt(0)
	s_barrier
	s_cmp_ge_i32 s12, s10
	s_cbranch_scc1 .LBB0_947
	v_add_u32_e32 v229, v224, v198
	ds_read_b128 v[130:133], v229
	ds_read_b128 v[134:137], v223
	ds_read_b128 v[146:149], v229 offset:32
	ds_read_b128 v[150:153], v223 offset:1024
	ds_read_b128 v[232:235], v229 offset:64
	ds_read_b128 v[236:239], v223 offset:2048
	ds_read_b128 v[240:243], v229 offset:96
	ds_read_b128 v[246:249], v223 offset:3072
	ds_read_b128 v[154:157], v229 offset:128
	ds_read_b128 v[158:161], v223 offset:4096
	s_waitcnt lgkmcnt(8)
	v_mfma_f32_32x32x16_bf16 v[130:145], v[130:133], v[134:137], 0
	v_lshl_add_u64 v[250:251], s[60:61], 0, v[214:215]
	global_load_dwordx4 v[166:169], v[250:251], off
	s_add_u32 s60, s60, s24
	s_addc_u32 s61, s61, s25
	s_waitcnt lgkmcnt(6)
	v_mfma_f32_32x32x16_bf16 v[130:145], v[146:149], v[150:153], v[130:145]
	s_waitcnt lgkmcnt(4)
	v_mfma_f32_32x32x16_bf16 v[130:145], v[232:235], v[236:239], v[130:145]
	ds_read_b128 v[232:235], v229 offset:160
	ds_read_b128 v[236:239], v223 offset:5120
	v_lshl_add_u64 v[252:253], s[60:61], 0, v[214:215]
	global_load_dwordx4 v[170:173], v[252:253], off
	s_add_u32 s60, s60, s24
	s_addc_u32 s61, s61, s25
	s_waitcnt lgkmcnt(4)
	v_mfma_f32_32x32x16_bf16 v[130:145], v[240:243], v[246:249], v[130:145]
	ds_read_b128 v[240:243], v229 offset:192
	ds_read_b128 v[246:249], v223 offset:6144
	s_waitcnt lgkmcnt(4)
	v_mfma_f32_32x32x16_bf16 v[130:145], v[154:157], v[158:161], v[130:145]
	ds_read_b128 v[154:157], v229 offset:224
	ds_read_b128 v[158:161], v223 offset:7168
	v_lshl_add_u64 v[250:251], s[60:61], 0, v[214:215]
	global_load_dwordx4 v[174:177], v[250:251], off
	s_add_u32 s60, s60, s24
	s_addc_u32 s61, s61, s25
	s_waitcnt lgkmcnt(4)
	v_mfma_f32_32x32x16_bf16 v[130:145], v[232:235], v[236:239], v[130:145]
	ds_read_b128 v[232:235], v229 offset:256
	ds_read_b128 v[236:239], v223 offset:8192
	s_waitcnt lgkmcnt(4)
	v_mfma_f32_32x32x16_bf16 v[130:145], v[240:243], v[246:249], v[130:145]
	ds_read_b128 v[240:243], v229 offset:288
	ds_read_b128 v[246:249], v223 offset:9216
	v_lshl_add_u64 v[252:253], s[60:61], 0, v[214:215]
	global_load_dwordx4 v[178:181], v[252:253], off
	s_add_u32 s60, s60, s24
	s_addc_u32 s61, s61, s25
	s_waitcnt lgkmcnt(4)
	v_mfma_f32_32x32x16_bf16 v[130:145], v[154:157], v[158:161], v[130:145]
	ds_read_b128 v[154:157], v229 offset:320
	ds_read_b128 v[158:161], v223 offset:10240
	s_waitcnt lgkmcnt(4)
	v_mfma_f32_32x32x16_bf16 v[130:145], v[232:235], v[236:239], v[130:145]
	ds_read_b128 v[232:235], v229 offset:352
	ds_read_b128 v[236:239], v223 offset:11264
	v_lshl_add_u64 v[250:251], s[60:61], 0, v[214:215]
	global_load_dwordx4 v[182:185], v[250:251], off
	s_add_u32 s60, s60, s24
	s_addc_u32 s61, s61, s25
	s_waitcnt lgkmcnt(4)
	v_mfma_f32_32x32x16_bf16 v[130:145], v[240:243], v[246:249], v[130:145]
	ds_read_b128 v[240:243], v229 offset:384
	ds_read_b128 v[246:249], v223 offset:12288
	s_waitcnt lgkmcnt(4)
	v_mfma_f32_32x32x16_bf16 v[130:145], v[154:157], v[158:161], v[130:145]
	ds_read_b128 v[154:157], v229 offset:416
	ds_read_b128 v[158:161], v223 offset:13312
	v_lshl_add_u64 v[252:253], s[60:61], 0, v[214:215]
	global_load_dwordx4 v[186:189], v[252:253], off
	s_add_u32 s60, s60, s24
	s_addc_u32 s61, s61, s25
	s_waitcnt lgkmcnt(4)
	v_mfma_f32_32x32x16_bf16 v[130:145], v[232:235], v[236:239], v[130:145]
	ds_read_b128 v[232:235], v229 offset:448
	ds_read_b128 v[236:239], v223 offset:14336
	s_waitcnt lgkmcnt(4)
	v_mfma_f32_32x32x16_bf16 v[130:145], v[240:243], v[246:249], v[130:145]
	ds_read_b128 v[240:243], v229 offset:480
	ds_read_b128 v[246:249], v223 offset:15360
	v_lshl_add_u64 v[250:251], s[60:61], 0, v[214:215]
	global_load_dwordx4 v[190:193], v[250:251], off
	s_add_u32 s60, s60, s24
	s_addc_u32 s61, s61, s25
	s_waitcnt lgkmcnt(4)
	v_mfma_f32_32x32x16_bf16 v[130:145], v[154:157], v[158:161], v[130:145]
	ds_read_b128 v[154:157], v229 offset:512
	ds_read_b128 v[158:161], v223 offset:16384
	s_waitcnt lgkmcnt(4)
	v_mfma_f32_32x32x16_bf16 v[130:145], v[232:235], v[236:239], v[130:145]
	ds_read_b128 v[232:235], v229 offset:544
	ds_read_b128 v[236:239], v223 offset:17408
	v_lshl_add_u64 v[252:253], s[60:61], 0, v[214:215]
	global_load_dwordx4 v[194:197], v[252:253], off
	s_waitcnt lgkmcnt(4)
	v_mfma_f32_32x32x16_bf16 v[130:145], v[240:243], v[246:249], v[130:145]
	s_waitcnt lgkmcnt(2)
	v_mfma_f32_32x32x16_bf16 v[130:145], v[154:157], v[158:161], v[130:145]
	v_cmp_lt_i32_e32 vcc, s11, v227
	v_lshl_add_u64 v[250:251], s[34:35], 0, v[212:213]
	s_and_saveexec_b64 s[6:7], vcc
	s_cbranch_execz .Lj3ld_norka
	global_load_dwordx4 v[162:165], v[250:251], off
.Lj3ld_norka:
	s_or_b64 exec, exec, s[6:7]
	s_waitcnt lgkmcnt(0)
	v_mfma_f32_32x32x16_bf16 v[130:145], v[232:235], v[236:239], v[130:145]
	s_nop 11
	v_mov_b32_e32 v146, v130
	v_mov_b32_e32 v147, v131
	v_max_f32_e32 v130, v146, v147
	v_max3_f32 v130, v130, v132, v133
	v_max3_f32 v130, v130, v134, v135
	v_max3_f32 v130, v130, v136, v137
	v_max3_f32 v130, v130, v138, v139
	v_max3_f32 v130, v130, v140, v141
	v_max3_f32 v130, v130, v142, v143
	v_max3_f32 v130, v130, v144, v145
	v_sub_f32_e32 v131, v230, v130
	v_cmp_gt_f32_e32 vcc, 0xc2200000, v131
	s_cbranch_vccnz .Llazy0_full
	ds_read_b64_tr_b16 v[232:233], v222
	ds_read_b64_tr_b16 v[234:235], v222 offset:4736
	ds_read_b64_tr_b16 v[236:237], v222 offset:64
	ds_read_b64_tr_b16 v[238:239], v222 offset:4800
	ds_read_b64_tr_b16 v[240:241], v222 offset:128
	ds_read_b64_tr_b16 v[242:243], v222 offset:4864
	ds_read_b64_tr_b16 v[246:247], v222 offset:192
	ds_read_b64_tr_b16 v[248:249], v222 offset:4928
	v_mov_b32_e32 v229, v230
	v_mov_b32_e32 v130, 1.0
	s_branch .LBB0_946
